# baseline (speedup 1.0000x reference)
; __device__ __forceinline__ void attn_load_kv(KVRegs& R, const bf16* Z, const bf16* KC, const bf16* VC, const float* sinks, int idx, int kvh, int tid) {
;     const bool sample = idx >= 256; const int c = idx & 31; const int row0 = idx * 64;
;     const int jmin = sample ? 0 : (c >= 2 ? 0 : 2 - c);
;     const int kr = tid >> 3, d0 = (tid & 7) * 8;
;     const v4u z = {0u, 0u, 0u, 0u};
;     R.k0 = z; R.k1 = z; R.k2 = z; R.v0 = z; R.v1 = z; R.v2 = z;
;     if (sample) {
;         const size_t off = ((size_t)((idx - 256) * 128 + kr)) * 256 + kvh * 64 + d0;
;         R.k0 = *(const v4u*)(KC + off); R.v0 = *(const v4u*)(VC + off); R.k1 = *(const v4u*)(KC + off + 64 * 256); R.v1 = *(const v4u*)(VC + off + 64 * 256);
;     } else {
;         const bf16* zr = Z + (size_t)(row0 - 128 + kr) * DIN + kvh * 64 + d0;
;         if (jmin <= 0) { R.k0 = *(const v4u*)(zr + 2048); R.v0 = *(const v4u*)(zr + 2304); }
;         if (jmin <= 1) { R.k1 = *(const v4u*)(zr + (size_t)64 * DIN + 2048); R.v1 = *(const v4u*)(zr + (size_t)64 * DIN + 2304); }
;     }
;     { const bf16* zr = Z + (size_t)(row0 + kr) * DIN + kvh * 64 + d0; R.k2 = *(const v4u*)(zr + 2048); R.v2 = *(const v4u*)(zr + 2304); }
;     { const int wid = tid >> 6, lane = tid & 63, g = wid >> 1, qh = wid & 1, r = lane & 31, h = lane >> 5;
;       const bf16* qp = Z + (size_t)(row0 + qh * 32 + r) * DIN + 1024 + (kvh * 4 + g) * 64 + 8 * h;
;       R.q0 = *(const bf16x8*)qp; R.q1 = *(const bf16x8*)(qp + 16); R.q2 = *(const bf16x8*)(qp + 32); R.q3 = *(const bf16x8*)(qp + 48); R.sink = sinks[kvh * 4 + g]; }
; }
; __device__ __forceinline__ void attn_units(LAS unsigned char* lds, const bf16* Z, const bf16* KC, const bf16* VC, const float* sinks, bf16* MIXIN, int bx, int G, int tid, int wid, int lane) {
;     ...
;     if (u < NATT) attn_load_kv(R, Z, KC, VC, sinks, u >> 2, u & 3, tid);
.LBB0_52:
	s_and_b64 s[30:31], s[18:19], exec
	s_cselect_b32 s30, 64, 0
	v_ashrrev_i32_e32 v160, 7, v180
	s_waitcnt lgkmcnt(0)
	s_add_u32 s28, s28, s30
	v_lshl_add_u32 v2, s13, 2, v160
	v_and_b32_e32 v11, 31, v180
	v_lshrrev_b32_e32 v0, 1, v180
	s_addc_u32 s29, s29, 0
	v_ashrrev_i32_e32 v3, 31, v2
	v_and_or_b32 v161, v0, 32, v11
	v_lshl_add_u64 v[4:5], v[2:3], 2, s[28:29]
	v_or_b32_e32 v0, s12, v161
	v_mov_b64_e32 v[8:9], s[8:9]
	global_load_dword v156, v[4:5], off
	v_mad_i64_i32 v[4:5], s[12:13], v0, s75, v[8:9]
	v_lshlrev_b32_e32 v2, 6, v2
	v_lshrrev_b32_e32 v0, 2, v180
	v_ashrrev_i32_e32 v3, 31, v2
	v_and_b32_e32 v10, 8, v0
	v_mad_i64_i32 v[6:7], s[12:13], v6, s75, v[8:9]
	s_lshl_b32 s88, s5, 1
	v_lshl_add_u64 v[2:3], v[2:3], 1, v[4:5]
	v_lshlrev_b32_e32 v0, 1, v10
	v_lshl_add_u64 v[6:7], v[6:7], 0, s[88:89]
	v_mov_b32_e32 v151, v1
	v_lshl_add_u64 v[2:3], v[2:3], 0, v[0:1]
	v_lshl_add_u64 v[6:7], v[6:7], 0, v[150:151]
	global_load_dwordx4 v[138:141], v[2:3], off offset:2144
	global_load_dwordx4 v[142:145], v[2:3], off offset:2112
	global_load_dwordx4 v[146:149], v[2:3], off offset:2080
	s_nop 0
	global_load_dwordx4 v[2:5], v[2:3], off offset:2048
	v_add_co_u32_e32 v6, vcc, s80, v6
	v_lshrrev_b32_e32 v8, 5, v206
	s_nop 0
	v_addc_co_u32_e32 v7, vcc, 0, v7, vcc
	global_load_dwordx4 v[118:121], v[6:7], off offset:512
	global_load_dwordx4 v[114:117], v[6:7], off
	v_and_b32_e32 v12, 64, v204
	s_movk_i32 s12, 0x90
	v_mul_u32_u24_e32 v6, 0x188, v159
	v_lshlrev_b32_e32 v7, 1, v158
	v_xor_b32_e32 v9, 32, v204
	v_lshlrev_b32_e32 v16, 4, v8
	v_add_u32_e32 v12, 64, v12
	v_mul_lo_u32 v0, v158, s12
	v_or_b32_e32 v13, 32, v206
	v_or_b32_e32 v14, 0x60, v206
	v_or_b32_e32 v15, 0xa0, v206
	v_add3_u32 v164, 0, v6, v7
	v_mad_u32_u24 v7, v11, s12, 0
	v_lshlrev_b32_e32 v17, 3, v8
	v_add_u32_e32 v19, 0, v16
	v_cmp_lt_i32_e32 vcc, v9, v12
	s_ashr_i32 s42, s4, 7
	v_readlane_b32 s4, v240, 1
	v_add3_u32 v163, 0, v0, v150
	v_mul_u32_u24_e32 v6, 0x90, v11
	v_lshlrev_b32_e32 v0, 2, v8
	v_mul_u32_u24_e32 v8, 0x90, v13
	v_mul_u32_u24_e32 v14, 0x90, v14
	v_mul_u32_u24_e32 v15, 0x90, v15
	v_mul_u32_u24_e32 v18, 0x188, v11
	v_mul_u32_u24_e32 v13, 0x188, v13
	v_cndmask_b32_e32 v9, v204, v9, vcc
	v_add_u32_e32 v167, v7, v16
	s_lshl_b32 s4, s4, 5
	v_sub_u32_e32 v7, v19, v17
	v_add_u32_e32 v162, 0xffff8000, v158
	s_mov_b32 s5, s2
	v_add_u32_e32 v165, 0x2400, v163
	v_add_u32_e32 v166, 0x4800, v163
	v_lshlrev_b32_e32 v152, 1, v10
	v_lshlrev_b32_e32 v168, 2, v9
	s_lshl_b32 s43, s2, 2
	s_lshl_b32 s44, s3, 2
	v_add_u32_e32 v169, v19, v8
	v_add_u32_e32 v170, v19, v6
	v_add_u32_e32 v171, v19, v14
	v_add_u32_e32 v172, v19, v15
	v_and_or_b32 v154, s4, 32, v11
	v_add_u32_e32 v173, v7, v18
	v_add_u32_e32 v174, v7, v13
	v_lshlrev_b32_e32 v0, 1, v0
	s_waitcnt vmcnt(6)
	v_mov_b32_e32 v151, v156
	s_waitcnt vmcnt(5)
	v_mov_b64_e32 v[134:135], v[138:139]
	s_waitcnt vmcnt(4)
	v_mov_b64_e32 v[130:131], v[142:143]
	s_waitcnt vmcnt(3)
	v_mov_b64_e32 v[126:127], v[146:147]
	s_waitcnt vmcnt(2)
	v_mov_b64_e32 v[124:125], v[4:5]
	v_mov_b64_e32 v[122:123], v[2:3]
	v_mov_b64_e32 v[128:129], v[148:149]
	v_mov_b64_e32 v[132:133], v[144:145]
	v_mov_b64_e32 v[136:137], v[140:141]
	v_lshrrev_b32_e32 v243, 6, v180
	v_mul_u32_u24_e32 v243, 0x1200, v243
	v_add_u32_e32 v243, 0xd000, v243
	v_and_b32_e32 v244, 31, v206
	v_lshrrev_b32_e32 v245, 5, v206
	v_mul_u32_u24_e32 v242, 0x90, v244
	v_lshl_add_u32 v242, v245, 3, v242
	v_add_u32_e32 v242, v242, v243
	v_lshrrev_b32_e32 v246, 3, v206
	v_and_b32_e32 v247, 7, v206
	v_mul_u32_u24_e32 v248, 0x90, v246
	v_lshl_add_u32 v248, v247, 4, v248
	v_add_u32_e32 v243, v248, v243
	v_sub_u32_e32 v244, v246, v244
	v_lshlrev_b32_e32 v244, 12, v244
	v_lshl_add_u32 v244, v247, 4, v244
	v_lshlrev_b32_e32 v245, 3, v245
	v_sub_u32_e32 v244, v244, v245
	v_ashrrev_i32_e32 v245, 31, v244
	s_waitcnt vmcnt(0)
	s_branch .LBB0_54

; __device__ __forceinline__ void attn_load_kv(KVRegs& R, const bf16* Z, const bf16* KC, const bf16* VC, const float* sinks, int idx, int kvh, int tid) {
;     const bool sample = idx >= 256; const int c = idx & 31; const int row0 = idx * 64;
;     const int jmin = sample ? 0 : (c >= 2 ? 0 : 2 - c);
;     const int kr = tid >> 3, d0 = (tid & 7) * 8;
;     const v4u z = {0u, 0u, 0u, 0u};
;     R.k0 = z; R.k1 = z; R.k2 = z; R.v0 = z; R.v1 = z; R.v2 = z;
;     if (sample) {
;         const size_t off = ((size_t)((idx - 256) * 128 + kr)) * 256 + kvh * 64 + d0;
;         R.k0 = *(const v4u*)(KC + off); R.v0 = *(const v4u*)(VC + off); R.k1 = *(const v4u*)(KC + off + 64 * 256); R.v1 = *(const v4u*)(VC + off + 64 * 256);
;     } else {
;         const bf16* zr = Z + (size_t)(row0 - 128 + kr) * DIN + kvh * 64 + d0;
;         if (jmin <= 0) { R.k0 = *(const v4u*)(zr + 2048); R.v0 = *(const v4u*)(zr + 2304); }
;         if (jmin <= 1) { R.k1 = *(const v4u*)(zr + (size_t)64 * DIN + 2048); R.v1 = *(const v4u*)(zr + (size_t)64 * DIN + 2304); }
;     }
; __device__ __forceinline__ void attn_units(LAS unsigned char* lds, const bf16* Z, const bf16* KC, const bf16* VC, const float* sinks, bf16* MIXIN, int bx, int G, int tid, int wid, int lane) {
;     ...
;         { const int kr = tid >> 3, d0 = (tid & 7) * 8;
;           attn_stage(Ks, Vt, R.k0, R.v0, kr, d0); attn_stage(Ks, Vt, R.k1, R.v1, 64 + kr, d0); attn_stage(Ks, Vt, R.k2, R.v2, 128 + kr, d0); }
;         const int g = wid >> 1, qh = wid & 1, r = lane & 31, h = lane >> 5;
;         const int head = kvh * 4 + g; const size_t qrow = (size_t)row0 + qh * 32 + r;
;         const bf16x8 bq[4] = {R.q0, R.q1, R.q2, R.q3};
;         const float sink = R.sink;
;         __syncthreads();
;         if (u + G < NATT) attn_load_kv(R, Z, KC, VC, sinks, (u + G) >> 2, (u + G) & 3, tid);
.LBB0_54:
	s_add_i32 s45, s5, s3
	s_cmpk_gt_i32 s45, 0x47f
	s_cselect_b64 s[30:31], -1, 0
	s_and_b64 vcc, exec, s[30:31]
	ds_write_b128 v163, v[98:101]
	ds_write_b16 v164, v102 offset:27648
	ds_write_b16_d16_hi v164, v102 offset:28040
	ds_write_b16 v164, v103 offset:28432
	ds_write_b16_d16_hi v164, v103 offset:28824
	ds_write_b16 v164, v104 offset:29216
	ds_write_b16_d16_hi v164, v104 offset:29608
	ds_write_b16 v164, v105 offset:30000
	ds_write_b16_d16_hi v164, v105 offset:30392
	ds_write_b128 v165, v[106:109]
	ds_write_b16 v164, v110 offset:27776
	ds_write_b16_d16_hi v164, v110 offset:28168
	ds_write_b16 v164, v111 offset:28560
	ds_write_b16_d16_hi v164, v111 offset:28952
	ds_write_b16 v164, v112 offset:29344
	ds_write_b16_d16_hi v164, v112 offset:29736
	ds_write_b16 v164, v113 offset:30128
	ds_write_b16_d16_hi v164, v113 offset:30520
	s_waitcnt vmcnt(4)
	ds_write_b128 v166, v[114:117]
	ds_write_b16 v164, v118 offset:27904
	ds_write_b16_d16_hi v164, v118 offset:28296
	ds_write_b16 v164, v119 offset:28688
	ds_write_b16_d16_hi v164, v119 offset:29080
	ds_write_b16 v164, v120 offset:29472
	ds_write_b16_d16_hi v164, v120 offset:29864
	ds_write_b16 v164, v121 offset:30256
	ds_write_b16_d16_hi v164, v121 offset:30648
	s_waitcnt lgkmcnt(0)
	s_barrier
	s_cbranch_vccnz .LBB0_62
	s_ashr_i32 s33, s45, 2
	s_and_b32 s4, s45, 3
	s_lshl_b32 s12, s33, 6
	s_lshl_b32 s13, s4, 6
	s_cmpk_lt_i32 s33, 0x100
	s_mov_b64 s[34:35], -1
	v_add_u32_e32 v8, s12, v158
	s_cbranch_scc0 .LBB0_59
	s_and_b32 s34, s33, 31
	s_sub_i32 s35, 2, s34
	v_add_u32_e32 v9, s12, v158
	s_cmp_lt_u32 s34, 2
	v_add_u32_e32 v10, 0xffffff80, v9
	v_mov_b64_e32 v[6:7], s[8:9]
	s_cselect_b32 s34, s35, 0
	v_mad_i64_i32 v[6:7], s[36:37], v10, s75, v[6:7]
	s_lshl_b32 s88, s13, 1
	v_lshl_add_u64 v[6:7], v[6:7], 0, s[88:89]
	v_mov_b32_e32 v151, v1
	s_cmp_lg_u32 s34, 0
	v_lshl_add_u64 v[6:7], v[6:7], 0, v[150:151]
	s_cbranch_scc0 .LBB0_72
	v_mov_b32_e32 v98, v1
	v_mov_b32_e32 v99, v1
	v_mov_b32_e32 v100, v1
	v_mov_b32_e32 v101, v1
	v_mov_b32_e32 v102, v1
	v_mov_b32_e32 v103, v1
	v_mov_b32_e32 v104, v1
	v_mov_b32_e32 v105, v1
	s_cmp_gt_u32 s34, 1
	s_cbranch_scc1 .LBB0_73
